# the static priority raise for waves 0-3 now also covers the dilated-attention item loop (reset moved to its exit)
# baseline (speedup 1.0000x reference)
.LBB0_550:
	s_setprio 0
	v_mov_b32_e32 v11, v234
	s_and_b64 vcc, exec, s[44:45]
	v_readfirstlane_b32 s7, v11
	s_cbranch_vccz .LBB0_574
	v_lshlrev_b32_e32 v1, 4, v11
	v_add_u32_e32 v2, 0x2000, v1
	v_ashrrev_i32_e32 v3, 31, v2
	v_lshrrev_b32_e32 v3, 22, v3
	v_add_u32_e32 v3, v2, v3
	v_ashrrev_i32_e32 v10, 10, v3
	v_mul_i32_i24_e32 v3, 0x400, v10
	v_sub_u32_e32 v2, v2, v3
	v_lshrrev_b32_e32 v3, 4, v2
	v_bitop3_b32 v2, v3, v2, 32 bitop3:0x6c
	v_ashrrev_i32_e32 v3, 31, v2
	v_lshrrev_b32_e32 v3, 26, v3
	v_add_u32_e32 v3, v2, v3
	v_lshlrev_b32_e32 v4, 3, v10
	v_ashrrev_i32_e32 v12, 6, v3
	v_and_b32_e32 v4, -16, v4
	v_add_u32_e32 v4, v12, v4
	v_and_b32_e32 v5, 3, v12
	s_mov_b32 s6, 0x3fffe0
	v_lshrrev_b32_e32 v6, 2, v4
	v_lshlrev_b32_e32 v7, 1, v4
	v_and_or_b32 v5, v4, s6, v5
	v_and_b32_e32 v6, 4, v6
	v_and_b32_e32 v7, 24, v7
	v_and_b32_e32 v3, 0xc0, v3
	v_or3_b32 v5, v5, v6, v7
	v_sub_u32_e32 v2, v2, v3
	v_mov_b32_e32 v7, 1
	v_lshlrev_b32_e32 v6, 5, v10
	v_ashrrev_i16_sdwa v2, v7, sext(v2) dst_sel:DWORD dst_unused:UNUSED_PAD src0_sel:DWORD src1_sel:BYTE_0
	v_and_b32_e32 v6, 32, v6
	v_bfe_i32 v2, v2, 0, 16
	v_add_lshl_u32 v2, v6, v2, 1
	v_lshl_add_u32 v130, v5, 10, v2
	v_and_b32_e32 v13, 0xffffffe0, v2
	v_and_b32_e32 v14, 30, v2
	v_bfe_i32 v2, v11, 27, 1
	v_lshrrev_b32_e32 v2, 22, v2
	v_add_u32_e32 v2, v1, v2
	v_and_b32_e32 v2, 0xfffffc00, v2
	v_lshl_add_u32 v3, v4, 10, v13
	v_sub_u32_e32 v1, v1, v2
	v_or_b32_e32 v132, v3, v14
	v_lshrrev_b32_e32 v2, 4, v1
	v_ashrrev_i32_e32 v3, 31, v11
	v_bitop3_b32 v1, v2, v1, 32 bitop3:0x6c
	v_lshrrev_b32_e32 v3, 26, v3
	v_ashrrev_i32_e32 v2, 31, v1
	v_add_u32_e32 v3, v11, v3
	v_lshrrev_b32_e32 v2, 26, v2
	v_ashrrev_i32_e32 v16, 6, v3
	v_add_u32_e32 v2, v1, v2
	v_lshlrev_b32_e32 v3, 3, v16
	s_add_u32 s0, s78, 0x16a00000
	v_ashrrev_i32_e32 v15, 6, v2
	v_and_b32_e32 v3, -16, v3
	s_addc_u32 s1, s79, 0
	v_add_u32_e32 v3, v15, v3
	v_and_b32_e32 v4, 3, v15
	v_readlane_b32 s19, v255, 24
	s_add_u32 s34, s78, 0x2a00000
	v_and_or_b32 v4, v3, s6, v4
	s_mul_hi_i32 s6, s19, 0x2aaaaaab
	s_addc_u32 s35, s79, 0
	s_lshr_b32 s8, s6, 31
	s_add_i32 s26, s6, s8
	s_mul_i32 s6, s26, 6
	s_sub_i32 s8, s19, s6
	s_bfe_i32 s6, s8, 0x80000
	s_mulk_i32 s6, 0x56
	s_bfe_u32 s10, s6, 0x1000f
	s_bfe_u32 s6, s6, 0x80008
	s_add_i32 s6, s6, s10
	s_ashr_i32 s9, s7, 6
	s_mul_i32 s10, s6, 3
	s_ashr_i32 s27, s26, 31
	s_ashr_i32 s14, s7, 8
	s_lshl_b32 s36, s9, 10
	s_sub_i32 s8, s8, s10
	s_lshl_b64 s[10:11], s[26:27], 19
	s_bfe_i64 s[12:13], s[6:7], 0x80000
	s_add_u32 s15, s0, s10
	s_addc_u32 s16, s1, s11
	s_bfe_i64 s[10:11], s[8:9], 0x80000
	v_lshrrev_b32_e32 v5, 2, v3
	v_lshlrev_b32_e32 v6, 1, v3
	v_and_b32_e32 v2, 0xc0, v2
	s_mul_i32 s18, s26, 0xc0000
	s_lshl_b64 s[10:11], s[10:11], 18
	v_and_b32_e32 v5, 4, v5
	v_and_b32_e32 v6, 24, v6
	v_sub_u32_e32 v1, v1, v2
	s_mul_hi_i32 s17, s26, 0xc0000
	s_add_u32 s18, s34, s18
	v_or3_b32 v4, v4, v5, v6
	v_lshlrev_b32_e32 v5, 5, v16
	v_ashrrev_i16_sdwa v1, v7, sext(v1) dst_sel:DWORD dst_unused:UNUSED_PAD src0_sel:DWORD src1_sel:BYTE_0
	s_addc_u32 s17, s35, s17
	v_and_b32_e32 v5, 32, v5
	v_bfe_i32 v1, v1, 0, 16
	s_add_u32 s46, s18, s10
	v_add_lshl_u32 v1, v5, v1, 1
	s_addc_u32 s47, s17, s11
	s_add_i32 s37, s36, 0
	v_lshl_add_u32 v134, v4, 10, v1
	s_add_i32 m0, s37, 0x10000
	s_lshl_b64 s[10:11], s[12:13], 18
	global_load_lds_dwordx4 v134, s[46:47]
	s_add_i32 m0, s37, 0x12000
	s_add_u32 s12, s46, 0x20000
	global_load_lds_dwordx4 v130, s[46:47]
	s_addc_u32 s13, s47, 0
	s_add_i32 m0, s37, 0x14000
	v_and_b32_e32 v17, 0xffffffe0, v1
	global_load_lds_dwordx4 v134, s[12:13]
	s_add_i32 m0, s37, 0x16000
	s_add_u32 s44, s15, s10
	v_lshl_add_u32 v2, v3, 10, v17
	v_and_b32_e32 v18, 30, v1
	s_addc_u32 s45, s16, s11
	s_add_i32 s52, s37, 0x2000
	v_or_b32_e32 v136, v2, v18
	global_load_lds_dwordx4 v130, s[12:13]
	s_mov_b32 m0, s37
	s_add_u32 s10, s44, 0x20000
	global_load_lds_dwordx4 v136, s[44:45]
	s_mov_b32 m0, s52
	s_addc_u32 s11, s45, 0
	s_add_i32 s53, s37, 0x4000
	global_load_lds_dwordx4 v132, s[44:45]
	s_mov_b32 m0, s53
	s_add_i32 s54, s37, 0x6000
	global_load_lds_dwordx4 v136, s[10:11]
	s_mov_b32 m0, s54
	v_mov_b32_e32 v135, v0
	global_load_lds_dwordx4 v132, s[10:11]
	v_mov_b32_e32 v131, v0
	v_mov_b32_e32 v137, v0
	v_mov_b32_e32 v133, v0
	s_cmp_eq_u32 s14, 1
	v_lshl_add_u64 v[8:9], s[46:47], 0, v[134:135]
	v_lshl_add_u64 v[6:7], s[46:47], 0, v[130:131]
	v_lshl_add_u64 v[2:3], s[44:45], 0, v[136:137]
	s_cselect_b64 s[10:11], -1, 0
	s_cmp_lg_u32 s14, 1
	v_lshl_add_u64 v[4:5], s[44:45], 0, v[132:133]
	s_cbranch_scc1 .LBB0_553
	s_barrier
